# E-j + nt (streaming) hint on the 8 bf16 weight stores of the P0 conversion loop
# speedup vs baseline: 1.0010x; 1.0010x over previous
; __device__ __forceinline__ void tr_finish(const Item& I, const f32x4 (&v)[8], LAS float* scr, int lane) {
;     const int lr = lane >> 3, lc = lane & 7;
;     f32x4 g0 = (f32x4){1.f, 1.f, 1.f, 1.f}, g1 = g0;
;     if (I.gain) { g0 = *(const GAS f32x4*)(I.gain + I.k0 + 8 * lc); g1 = *(const GAS f32x4*)(I.gain + I.k0 + 8 * lc + 4); }
; #pragma unroll
;     for (int i = 0; i < 8; ++i) { LAS float* s = scr + (i * 8 + lr) * 33 + 4 * lc; s[0] = v[i][0]; s[1] = v[i][1]; s[2] = v[i][2]; s[3] = v[i][3]; }
;     LDS_WAIT(); asm volatile("" ::: "memory");
; #pragma unroll
;     for (int j = 0; j < 4; ++j) { const int n = lr + 8 * j; const LAS float* s = scr + (8 * lc) * 33 + n;
;         v4u o; o.x = pg8::cvt_pk_bf16(s[0 * 33] * g0[0], s[1 * 33] * g0[1]); o.y = pg8::cvt_pk_bf16(s[2 * 33] * g0[2], s[3 * 33] * g0[3]); o.z = pg8::cvt_pk_bf16(s[4 * 33] * g1[0], s[5 * 33] * g1[1]); o.w = pg8::cvt_pk_bf16(s[6 * 33] * g1[2], s[7 * 33] * g1[3]);
;         *(GAS v4u*)(I.dst + (size_t)(I.drow + n) * I.ldd + I.dk0 + 8 * lc) = o; }
;     LDS_WAIT(); asm volatile("" ::: "memory");
; }
; __device__ __forceinline__ Item decode_item(KArgP argp, unsigned char* ws, int l, int it) {
;     Item I; int r = it;
;     if (r < 2 * I_GU) { const int f = r >= I_GU; r -= f * I_GU; const int kb = r / 352, nb = r - kb * 352, n0 = 32 * nb, t = n0 >> 8, s = (n0 >> 7) & 1, j0 = n0 & 127;
;         I.src = argp->in[f ? (s ? 18 : 17) : (s ? 4 : 3)] + (size_t)l * DM * DFF; I.ldsrc = DFF; I.scol0 = 128 * t + j0; I.k0 = 64 * kb; I.gain = argp->in[f ? 16 : 2] + l * DM;
;         I.dst = (bf16*)(ws + WS_WGU + (size_t)(l * 2 + f) * SZ_WGU); I.ldd = DM; I.drow = n0; I.dk0 = 64 * kb; return I; }
;     r -= 2 * I_GU;
;     if (r < 2 * I_DN) { const int f = r >= I_DN; r -= f * I_DN; const int kb = r >> 6, nb = r & 63;
;         I.src = argp->in[f ? 19 : 5] + (size_t)l * DFF * DM; I.ldsrc = DM; I.scol0 = 32 * nb; I.k0 = 64 * kb; I.gain = nullptr;
;         I.dst = (bf16*)(ws + WS_WDN + (size_t)(l * 2 + f) * SZ_WDN); I.ldd = DFF; I.drow = 32 * nb; I.dk0 = 64 * kb; return I; }
;     r -= 2 * I_DN;
;     if (r < I_WIN) { const int kb = r >> 7, nb = r & 127, n0 = 32 * nb, pn = n0 >> 8; int scol0 = n0;
;         if (pn >= 4 && pn < 12) { const int tcol = n0 & 255, bj = tcol >> 7, wc = (tcol >> 5) & 3, vec = 4 * (pn & 3) + wc; scol0 = (pn < 8 ? 1024 : 2048) + vec * 64 + 32 * bj; }
.LBB0_47:
	v_add_u32_e32 v92, 0x420, v91
	v_add_u32_e32 v93, 0x428, v91
	v_add_u32_e32 v94, 0x840, v91
	v_add_u32_e32 v95, 0x848, v91
	v_add_u32_e32 v96, 0xc60, v91
	v_add_u32_e32 v97, 0xc68, v91
	v_add_u32_e32 v98, 0x1080, v91
	v_add_u32_e32 v99, 0x1088, v91
	v_add_u32_e32 v100, 0x14a0, v91
	v_add_u32_e32 v101, 0x14a8, v91
	v_add_u32_e32 v102, 0x18c0, v91
	v_add_u32_e32 v103, 0x18c8, v91
	v_add_u32_e32 v104, 0x1ce0, v91
	v_add_u32_e32 v105, 0x1ce8, v91
	s_waitcnt vmcnt(7)
	ds_write2_b32 v91, v4, v5 offset1:1
	ds_write2_b32 v91, v6, v7 offset0:2 offset1:3
	s_waitcnt vmcnt(6)
	ds_write2_b32 v92, v0, v1 offset1:1
	ds_write2_b32 v93, v2, v3 offset1:1
	s_waitcnt vmcnt(5)
	ds_write2_b32 v94, v12, v13 offset1:1
	ds_write2_b32 v95, v14, v15 offset1:1
	s_waitcnt vmcnt(4)
	ds_write2_b32 v96, v8, v9 offset1:1
	ds_write2_b32 v97, v10, v11 offset1:1
	s_waitcnt vmcnt(3)
	ds_write2_b32 v98, v20, v21 offset1:1
	ds_write2_b32 v99, v22, v23 offset1:1
	s_waitcnt vmcnt(2)
	ds_write2_b32 v100, v16, v17 offset1:1
	ds_write2_b32 v101, v18, v19 offset1:1
	s_waitcnt vmcnt(1)
	ds_write2_b32 v102, v28, v29 offset1:1
	ds_write2_b32 v103, v30, v31 offset1:1
	s_waitcnt vmcnt(0)
	ds_write2_b32 v104, v24, v25 offset1:1
	ds_write2_b32 v105, v26, v27 offset1:1
	s_waitcnt lgkmcnt(0)
	ds_read2_b32 v[106:107], v90 offset1:33
	s_ashr_i32 s5, s4, 31
	s_andn2_b64 vcc, exec, s[26:27]
	s_waitcnt lgkmcnt(0)
	v_mul_f32_e32 v106, v68, v106
	v_mul_f32_e32 v107, v69, v107
	v_cvt_pk_bf16_f32 v106, v106, v107
	ds_read2_b32 v[108:109], v90 offset0:66 offset1:99
	s_waitcnt lgkmcnt(0)
	v_mul_f32_e32 v107, v70, v108
	v_mul_f32_e32 v108, v71, v109
	v_cvt_pk_bf16_f32 v107, v107, v108
	ds_read2_b32 v[108:109], v90 offset0:132 offset1:165
	s_waitcnt lgkmcnt(0)
	v_mul_f32_e32 v108, v64, v108
	v_mul_f32_e32 v109, v65, v109
	v_cvt_pk_bf16_f32 v108, v108, v109
	ds_read2_b32 v[110:111], v90 offset0:198 offset1:231
	s_waitcnt lgkmcnt(0)
	v_mul_f32_e32 v109, v66, v110
	v_mul_f32_e32 v110, v67, v111
	v_cvt_pk_bf16_f32 v109, v109, v110
	v_add_u32_e32 v110, s3, v82
	v_ashrrev_i32_e32 v113, 31, v110
	v_mad_u64_u32 v[110:111], s[28:29], v110, s42, 0
	v_mov_b32_e32 v112, v111
	v_mad_u64_u32 v[112:113], s[28:29], v113, s42, v[112:113]
	v_mov_b32_e32 v111, v112
	ds_read2_b32 v[112:113], v90 offset0:8 offset1:41
	v_lshl_add_u64 v[110:111], v[110:111], 1, v[78:79]
	s_lshl_b64 s[28:29], s[4:5], 1
	v_lshl_add_u64 v[110:111], v[110:111], 0, s[28:29]
	v_lshl_add_u64 v[110:111], v[110:111], 0, v[74:75]
	global_store_dwordx4 v[110:111], v[106:109], off nt
	s_waitcnt lgkmcnt(0)
	s_nop 0
	v_mul_f32_e32 v106, v68, v112
	v_mul_f32_e32 v107, v69, v113
	v_cvt_pk_bf16_f32 v106, v106, v107
	ds_read2_b32 v[108:109], v90 offset0:74 offset1:107
	s_waitcnt lgkmcnt(0)
	v_mul_f32_e32 v107, v70, v108
	v_mul_f32_e32 v108, v71, v109
	v_cvt_pk_bf16_f32 v107, v107, v108
	ds_read2_b32 v[108:109], v90 offset0:140 offset1:173
	s_waitcnt lgkmcnt(0)
	v_mul_f32_e32 v108, v64, v108
	v_mul_f32_e32 v109, v65, v109
	v_cvt_pk_bf16_f32 v108, v108, v109
	ds_read2_b32 v[110:111], v90 offset0:206 offset1:239
	s_waitcnt lgkmcnt(0)
	v_mul_f32_e32 v109, v66, v110
	v_mul_f32_e32 v110, v67, v111
	v_cvt_pk_bf16_f32 v109, v109, v110
	v_add_u32_e32 v110, s3, v83
	v_ashrrev_i32_e32 v113, 31, v110
	v_mad_u64_u32 v[110:111], s[30:31], v110, s42, 0
	v_mov_b32_e32 v112, v111
	v_mad_u64_u32 v[112:113], s[30:31], v113, s42, v[112:113]
	v_mov_b32_e32 v111, v112
	ds_read2_b32 v[112:113], v90 offset0:16 offset1:49
	v_lshl_add_u64 v[110:111], v[110:111], 1, v[78:79]
	v_lshl_add_u64 v[110:111], v[110:111], 0, s[28:29]
	v_lshl_add_u64 v[110:111], v[110:111], 0, v[74:75]
	global_store_dwordx4 v[110:111], v[106:109], off nt
	s_waitcnt lgkmcnt(0)
	s_nop 0
	v_mul_f32_e32 v106, v68, v112
	v_mul_f32_e32 v107, v69, v113
	v_cvt_pk_bf16_f32 v106, v106, v107
	ds_read2_b32 v[108:109], v90 offset0:82 offset1:115
	s_waitcnt lgkmcnt(0)
	v_mul_f32_e32 v107, v70, v108
	v_mul_f32_e32 v108, v71, v109
	v_cvt_pk_bf16_f32 v107, v107, v108
	ds_read2_b32 v[108:109], v90 offset0:148 offset1:181
	s_waitcnt lgkmcnt(0)
	v_mul_f32_e32 v108, v64, v108
	v_mul_f32_e32 v109, v65, v109
	v_cvt_pk_bf16_f32 v108, v108, v109
	ds_read2_b32 v[110:111], v90 offset0:214 offset1:247
	s_waitcnt lgkmcnt(0)
	v_mul_f32_e32 v109, v66, v110
	v_mul_f32_e32 v110, v67, v111
	v_cvt_pk_bf16_f32 v109, v109, v110
	v_add_u32_e32 v110, s3, v84
	v_ashrrev_i32_e32 v113, 31, v110
	v_mad_u64_u32 v[110:111], s[30:31], v110, s42, 0
	v_mov_b32_e32 v112, v111
	v_mad_u64_u32 v[112:113], s[30:31], v113, s42, v[112:113]
	v_mov_b32_e32 v111, v112
	ds_read2_b32 v[112:113], v90 offset0:24 offset1:57
	v_lshl_add_u64 v[110:111], v[110:111], 1, v[78:79]
	v_lshl_add_u64 v[110:111], v[110:111], 0, s[28:29]
	v_lshl_add_u64 v[110:111], v[110:111], 0, v[74:75]
	global_store_dwordx4 v[110:111], v[106:109], off nt
	s_waitcnt lgkmcnt(0)
	v_mul_f32_e32 v68, v68, v112
	v_mul_f32_e32 v69, v69, v113
	v_cvt_pk_bf16_f32 v68, v68, v69
	ds_read2_b32 v[106:107], v90 offset0:90 offset1:123
	s_waitcnt lgkmcnt(0)
	v_mul_f32_e32 v69, v70, v106
	v_mul_f32_e32 v70, v71, v107
	v_cvt_pk_bf16_f32 v69, v69, v70
	ds_read2_b32 v[70:71], v90 offset0:156 offset1:189
	s_waitcnt lgkmcnt(0)
	v_mul_f32_e32 v64, v64, v70
	v_mul_f32_e32 v65, v65, v71
	v_cvt_pk_bf16_f32 v70, v64, v65
	ds_read2_b32 v[64:65], v90 offset0:222 offset1:255
	s_waitcnt lgkmcnt(0)
	v_mul_f32_e32 v64, v66, v64
	v_mul_f32_e32 v65, v67, v65
	v_cvt_pk_bf16_f32 v71, v64, v65
	v_add_u32_e32 v64, s3, v85
	v_ashrrev_i32_e32 v67, 31, v64
	v_mad_u64_u32 v[64:65], s[30:31], v64, s42, 0
	v_mov_b32_e32 v66, v65
	v_mad_u64_u32 v[66:67], s[30:31], v67, s42, v[66:67]
	v_mov_b32_e32 v65, v66
	v_lshl_add_u64 v[64:65], v[64:65], 1, v[78:79]
	v_lshl_add_u64 v[64:65], v[64:65], 0, s[28:29]
	v_lshl_add_u64 v[64:65], v[64:65], 0, v[74:75]
	global_store_dwordx4 v[64:65], v[68:71], off nt
	s_waitcnt lgkmcnt(0)
	s_cbranch_vccnz .LBB0_28
	s_add_i32 s5, s43, s23
	s_cmp_gt_i32 s5, 0x26fff
	s_cbranch_scc1 .LBB0_63
	s_mul_hi_i32 s3, s5, 0xd20d20d3
	s_add_i32 s3, s3, s5
	s_lshr_b32 s4, s3, 31
	s_ashr_i32 s31, s3, 15
	s_add_i32 s31, s31, s4
	s_mul_i32 s3, s31, 0xffff6400
	s_sub_i32 s16, 3, s31
	s_add_i32 s38, s5, s3
	s_cmpk_gt_i32 s38, 0x57ff
	s_cbranch_scc0 .LBB0_60
	s_cmpk_gt_u32 s38, 0x83ff
	s_mov_b64 s[34:35], -1
	s_cbranch_scc0 .LBB0_57
	s_cmpk_gt_u32 s38, 0x93ff
	s_mov_b64 s[6:7], -1
	s_cbranch_scc0 .LBB0_53
	s_load_dwordx2 s[6:7], s[10:11], 0x78
	s_and_b32 s3, s38, 0x7fffffc0
	s_lshl_b64 s[26:27], s[16:17], 24
	s_add_i32 s4, s3, 0xffff6c00
	s_waitcnt lgkmcnt(0)
	s_add_u32 s26, s6, s26
	s_addc_u32 s27, s7, s27
	s_add_i32 s3, s44, s52
	s_and_b32 s3, s3, 0x7e0
	s_lshl_b64 s[6:7], s[16:17], 23
	s_add_u32 s36, s13, s6
	s_addc_u32 s37, s15, s7
	s_mov_b64 s[6:7], 0

; __device__ __forceinline__ unsigned cvt_pk_bf16(float lo, float hi) { unsigned r; asm volatile("v_cvt_pk_bf16_f32 %0, %1, %2" : "=v"(r) : "v"(lo), "v"(hi)); return r; }
; #define GAS __attribute__((address_space(1)))
; #define LAS __attribute__((address_space(3)))
; #define LDS_WAIT() asm volatile("s_waitcnt lgkmcnt(0)" ::: "memory")
; __device__ __forceinline__ Item decode_global(KArgP argp, unsigned char* ws, int g) { const int q = g / I_L; return decode_item(argp, ws, DEPTH - 1 - q, g - q * I_L); }
; __device__ __forceinline__ void tr_finish(const Item& I, const f32x4 (&v)[8], LAS float* scr, int lane) {
;     const int lr = lane >> 3, lc = lane & 7;
;     f32x4 g0 = (f32x4){1.f, 1.f, 1.f, 1.f}, g1 = g0;
;     if (I.gain) { g0 = *(const GAS f32x4*)(I.gain + I.k0 + 8 * lc); g1 = *(const GAS f32x4*)(I.gain + I.k0 + 8 * lc + 4); }
; #pragma unroll
;     for (int i = 0; i < 8; ++i) { LAS float* s = scr + (i * 8 + lr) * 33 + 4 * lc; s[0] = v[i][0]; s[1] = v[i][1]; s[2] = v[i][2]; s[3] = v[i][3]; }
;     LDS_WAIT(); asm volatile("" ::: "memory");
; #pragma unroll
;     for (int j = 0; j < 4; ++j) { const int n = lr + 8 * j; const LAS float* s = scr + (8 * lc) * 33 + n;
;         v4u o; o.x = pg8::cvt_pk_bf16(s[0 * 33] * g0[0], s[1 * 33] * g0[1]); o.y = pg8::cvt_pk_bf16(s[2 * 33] * g0[2], s[3 * 33] * g0[3]); o.z = pg8::cvt_pk_bf16(s[4 * 33] * g1[0], s[5 * 33] * g1[1]); o.w = pg8::cvt_pk_bf16(s[6 * 33] * g1[2], s[7 * 33] * g1[3]);
;         *(GAS v4u*)(I.dst + (size_t)(I.drow + n) * I.ldd + I.dk0 + 8 * lc) = o; }
;     LDS_WAIT(); asm volatile("" ::: "memory");
; }
; __device__ __forceinline__ void p0_prologue(KArgP argp, LAS unsigned char* lds, int vcu, int G, int wave, int lane) {
;     ...
;             it += NGW; const bool m1 = it < DEPTH * I_L; if (m1) { b = decode_global(argp, ws, it); tr_load(b, vb, lane); }
;             tr_finish(a, va, scr, lane); if (!m1) break;
;             it += NGW; const bool m2 = it < DEPTH * I_L; if (m2) { a = decode_global(argp, ws, it); tr_load(a, va, lane); }
;             tr_finish(b, vb, scr, lane); if (!m2) break;
.LBB0_66:
	ds_write2_b32 v91, v36, v37 offset1:1
	ds_write2_b32 v91, v38, v39 offset0:2 offset1:3
	ds_write2_b32 v92, v32, v33 offset1:1
	ds_write2_b32 v93, v34, v35 offset1:1
	ds_write2_b32 v94, v44, v45 offset1:1
	ds_write2_b32 v95, v46, v47 offset1:1
	ds_write2_b32 v96, v40, v41 offset1:1
	ds_write2_b32 v97, v42, v43 offset1:1
	ds_write2_b32 v98, v52, v53 offset1:1
	ds_write2_b32 v99, v54, v55 offset1:1
	ds_write2_b32 v100, v48, v49 offset1:1
	ds_write2_b32 v101, v50, v51 offset1:1
	ds_write2_b32 v102, v60, v61 offset1:1
	ds_write2_b32 v103, v62, v63 offset1:1
	ds_write2_b32 v104, v56, v57 offset1:1
	ds_write2_b32 v105, v58, v59 offset1:1
	s_waitcnt lgkmcnt(0)
	ds_read2_b32 v[92:93], v90 offset1:33
	s_ashr_i32 s23, s22, 31
	s_add_i32 s52, s52, s45
	s_add_i32 s53, s53, s46
	s_add_i32 s54, s54, s47
	s_waitcnt vmcnt(0) lgkmcnt(0)
	v_mul_f32_e32 v92, v68, v92
	v_mul_f32_e32 v93, v69, v93
	v_cvt_pk_bf16_f32 v92, v92, v93
	ds_read2_b32 v[94:95], v90 offset0:66 offset1:99
	s_add_i32 s55, s55, s45
	s_waitcnt lgkmcnt(0)
	v_mul_f32_e32 v93, v70, v94
	v_mul_f32_e32 v94, v71, v95
	v_cvt_pk_bf16_f32 v93, v93, v94
	ds_read2_b32 v[94:95], v90 offset0:132 offset1:165
	s_waitcnt lgkmcnt(0)
	v_mul_f32_e32 v94, v64, v94
	v_mul_f32_e32 v95, v65, v95
	v_cvt_pk_bf16_f32 v94, v94, v95
	ds_read2_b32 v[96:97], v90 offset0:198 offset1:231
	s_waitcnt lgkmcnt(0)
	v_mul_f32_e32 v95, v66, v96
	v_mul_f32_e32 v96, v67, v97
	v_cvt_pk_bf16_f32 v95, v95, v96
	v_add_u32_e32 v96, s56, v82
	v_ashrrev_i32_e32 v99, 31, v96
	v_mad_u64_u32 v[96:97], s[26:27], v96, s57, 0
	v_mov_b32_e32 v98, v97
	v_mad_u64_u32 v[98:99], s[26:27], v99, s57, v[98:99]
	v_mov_b32_e32 v97, v98
	ds_read2_b32 v[98:99], v90 offset0:8 offset1:41
	v_lshl_add_u64 v[96:97], v[96:97], 1, v[80:81]
	s_lshl_b64 s[26:27], s[22:23], 1
	v_lshl_add_u64 v[96:97], v[96:97], 0, s[26:27]
	v_lshl_add_u64 v[96:97], v[96:97], 0, v[74:75]
	global_store_dwordx4 v[96:97], v[92:95], off nt
	s_add_i32 s23, s58, s14
	s_cmp_gt_i32 s23, 0x26fff
	s_waitcnt lgkmcnt(0)
	v_mul_f32_e32 v92, v68, v98
	v_mul_f32_e32 v93, v69, v99
	v_cvt_pk_bf16_f32 v92, v92, v93
	ds_read2_b32 v[94:95], v90 offset0:74 offset1:107
	s_waitcnt lgkmcnt(0)
	v_mul_f32_e32 v93, v70, v94
	v_mul_f32_e32 v94, v71, v95
	v_cvt_pk_bf16_f32 v93, v93, v94
	ds_read2_b32 v[94:95], v90 offset0:140 offset1:173
	s_waitcnt lgkmcnt(0)
	v_mul_f32_e32 v94, v64, v94
	v_mul_f32_e32 v95, v65, v95
	v_cvt_pk_bf16_f32 v94, v94, v95
	ds_read2_b32 v[96:97], v90 offset0:206 offset1:239
	s_waitcnt lgkmcnt(0)
	v_mul_f32_e32 v95, v66, v96
	v_mul_f32_e32 v96, v67, v97
	v_cvt_pk_bf16_f32 v95, v95, v96
	v_add_u32_e32 v96, s56, v83
	v_ashrrev_i32_e32 v99, 31, v96
	v_mad_u64_u32 v[96:97], s[28:29], v96, s57, 0
	v_mov_b32_e32 v98, v97
	v_mad_u64_u32 v[98:99], s[28:29], v99, s57, v[98:99]
	v_mov_b32_e32 v97, v98
	ds_read2_b32 v[98:99], v90 offset0:16 offset1:49
	v_lshl_add_u64 v[96:97], v[96:97], 1, v[80:81]
	v_lshl_add_u64 v[96:97], v[96:97], 0, s[26:27]
	v_lshl_add_u64 v[96:97], v[96:97], 0, v[74:75]
	global_store_dwordx4 v[96:97], v[92:95], off nt
	s_waitcnt lgkmcnt(0)
	s_nop 0
	v_mul_f32_e32 v92, v68, v98
	v_mul_f32_e32 v93, v69, v99
	v_cvt_pk_bf16_f32 v92, v92, v93
	ds_read2_b32 v[94:95], v90 offset0:82 offset1:115
	s_waitcnt lgkmcnt(0)
	v_mul_f32_e32 v93, v70, v94
	v_mul_f32_e32 v94, v71, v95
	v_cvt_pk_bf16_f32 v93, v93, v94
	ds_read2_b32 v[94:95], v90 offset0:148 offset1:181
	s_waitcnt lgkmcnt(0)
	v_mul_f32_e32 v94, v64, v94
	v_mul_f32_e32 v95, v65, v95
	v_cvt_pk_bf16_f32 v94, v94, v95
	ds_read2_b32 v[96:97], v90 offset0:214 offset1:247
	s_waitcnt lgkmcnt(0)
	v_mul_f32_e32 v95, v66, v96
	v_mul_f32_e32 v96, v67, v97
	v_cvt_pk_bf16_f32 v95, v95, v96
	v_add_u32_e32 v96, s56, v84
	v_ashrrev_i32_e32 v99, 31, v96
	v_mad_u64_u32 v[96:97], s[28:29], v96, s57, 0
	v_mov_b32_e32 v98, v97
	v_mad_u64_u32 v[98:99], s[28:29], v99, s57, v[98:99]
	v_mov_b32_e32 v97, v98
	ds_read2_b32 v[98:99], v90 offset0:24 offset1:57
	v_lshl_add_u64 v[96:97], v[96:97], 1, v[80:81]
	v_lshl_add_u64 v[96:97], v[96:97], 0, s[26:27]
	v_lshl_add_u64 v[96:97], v[96:97], 0, v[74:75]
	global_store_dwordx4 v[96:97], v[92:95], off nt
	s_waitcnt lgkmcnt(0)
	v_mul_f32_e32 v68, v68, v98
	v_mul_f32_e32 v69, v69, v99
	v_cvt_pk_bf16_f32 v68, v68, v69
	ds_read2_b32 v[92:93], v90 offset0:90 offset1:123
	s_waitcnt lgkmcnt(0)
	v_mul_f32_e32 v69, v70, v92
	v_mul_f32_e32 v70, v71, v93
	v_cvt_pk_bf16_f32 v69, v69, v70
	ds_read2_b32 v[70:71], v90 offset0:156 offset1:189
	s_waitcnt lgkmcnt(0)
	v_mul_f32_e32 v64, v64, v70
	v_mul_f32_e32 v65, v65, v71
	v_cvt_pk_bf16_f32 v70, v64, v65
	ds_read2_b32 v[64:65], v90 offset0:222 offset1:255
	s_waitcnt lgkmcnt(0)
	v_mul_f32_e32 v64, v66, v64
	v_mul_f32_e32 v65, v67, v65
	v_cvt_pk_bf16_f32 v71, v64, v65
	v_add_u32_e32 v64, s56, v85
	v_ashrrev_i32_e32 v67, 31, v64
	v_mad_u64_u32 v[64:65], s[28:29], v64, s57, 0
	v_mov_b32_e32 v66, v65
	v_mad_u64_u32 v[66:67], s[28:29], v67, s57, v[66:67]
	v_mov_b32_e32 v65, v66
	v_lshl_add_u64 v[64:65], v[64:65], 1, v[80:81]
	v_lshl_add_u64 v[64:65], v[64:65], 0, s[26:27]
	v_lshl_add_u64 v[64:65], v[64:65], 0, v[74:75]
	global_store_dwordx4 v[64:65], v[68:71], off nt
	s_waitcnt lgkmcnt(0)
	s_cselect_b64 s[26:27], -1, 0
	s_and_b64 vcc, exec, s[26:27]
	s_cbranch_vccz .LBB0_29
